# v24
# speedup vs baseline: 1.0457x; 1.0023x over previous
.LBB0_844:
	s_add_u32 s18, s14, s6
	s_addc_u32 s19, s15, s7
	global_load_dwordx4 v[4:7], v209, s[18:19] offset:16
	global_load_dwordx4 v[8:11], v209, s[18:19]
	s_add_u32 s18, s16, s6
	s_addc_u32 s19, s17, s7
	global_load_dwordx4 v[12:15], v209, s[18:19]
	global_load_dwordx4 v[16:19], v209, s[18:19] offset:16
	s_add_u32 s6, s6, 32
	s_addc_u32 s7, s7, 0
	s_cmpk_eq_i32 s6, 0x400
	s_waitcnt vmcnt(2)
	v_max3_f32 v2, v2, |v8|, |v9|
	v_max3_f32 v2, v2, |v10|, |v11|
	s_waitcnt vmcnt(1)
	v_max3_f32 v1, v1, |v12|, |v13|
	v_max3_f32 v1, v1, |v14|, |v15|
	v_max3_f32 v2, v2, |v4|, |v5|
	s_waitcnt vmcnt(0)
	v_max3_f32 v1, v1, |v16|, |v17|
	v_max3_f32 v2, v2, |v6|, |v7|
	v_max3_f32 v1, v1, |v18|, |v19|
	s_cbranch_scc0 .LBB0_844
	v_mul_f32_e32 v2, 0x41b8aa3b, v2
	v_mul_f32_e32 v1, v1, v2
	s_mov_b32 s47, s2
	s_cmpk_gt_i32 s47, 0x7ff
	v_readfirstlane_b32 s16, v1
	s_cbranch_scc1 .LBB0_851
	s_lshl_b32 s6, s52, 24
	s_add_u32 s14, s10, 0x12000000
	s_addc_u32 s15, s11, 0
	s_add_u32 s17, s10, s6
	s_addc_u32 s18, s11, 0
	s_add_u32 s56, s17, 0x6800000
	s_addc_u32 s57, s18, 0
	v_and_b32_e32 v9, 64, v252
	s_add_u32 s58, s17, 0x4800000
	v_xor_b32_e32 v8, 32, v252
	v_add_u32_e32 v9, 64, v9
	v_or_b32_e32 v1, s33, v0
	s_addc_u32 s59, s18, 0
	s_lshl_b32 s36, s52, 8
	v_cmp_lt_i32_e32 vcc, v8, v9
	v_bfe_u32 v5, v0, 5, 1
	v_and_b32_e32 v7, 31, v0
	v_ashrrev_i32_e32 v6, 2, v1
	s_movk_i32 s17, 0xffe0
	v_cndmask_b32_e32 v8, v252, v8, vcc
	s_lshl_b64 s[18:19], s[36:37], 2
	v_ashrrev_i32_e32 v3, 6, v1
	v_and_b32_e32 v200, 0xffffffe0, v6
	v_bfi_b32 v207, s17, v6, v0
	v_lshlrev_b32_e32 v6, 3, v5
	v_lshlrev_b32_e32 v215, 2, v8
	s_add_u32 s4, s4, s18
	v_mul_u32_u24_e32 v8, 0x210, v7
	v_lshlrev_b32_e32 v5, 4, v5
	s_addc_u32 s5, s5, s19
	v_and_b32_e32 v208, 32, v0
	v_add3_u32 v228, 0, v8, v5
	v_lshlrev_b32_e32 v5, 7, v3
	v_lshl_add_u64 v[202:203], s[4:5], 0, v[208:209]
	v_lshlrev_b32_e32 v14, 4, v252
	global_load_dwordx4 v[10:13], v14, s[4:5]
	v_add_u32_e32 v14, 0x1f000, v14
	v_add_u32_e32 v202, 0x1f000, v208
	s_waitcnt vmcnt(0)
	ds_write_b128 v14, v[10:13]
	s_waitcnt lgkmcnt(0)
	s_barrier
	v_and_b32_e32 v5, 0x80, v5
	s_movk_i32 s4, 0x2200
	v_ashrrev_i32_e32 v196, 3, v1
	v_ashrrev_i32_e32 v198, 5, v1
	v_lshlrev_b32_e32 v4, 3, v1
	v_mul_lo_u32 v3, v3, s4
	v_lshlrev_b32_e32 v1, 4, v1
	v_lshlrev_b32_e32 v208, 1, v5
	v_add_u32_e32 v3, 0, v3
	s_movk_i32 s4, 0x110
	v_and_b32_e32 v8, 0xf0, v1
	v_lshl_add_u64 v[10:11], s[10:11], 0, v[208:209]
	v_mov_b32_e32 v9, v209
	v_ashrrev_i32_e32 v199, 31, v198
	v_or_b32_e32 v14, v5, v7
	v_mad_u32_u24 v7, v7, s4, v3
	v_add_u32_e32 v1, v3, v8
	v_lshl_add_u64 v[8:9], v[10:11], 0, v[8:9]
	s_mov_b64 s[4:5], 0x2a000000
	v_lshl_add_u64 v[204:205], v[8:9], 0, s[4:5]
	v_mul_u32_u24_e32 v5, 0x90, v14
	v_lshlrev_b64 v[8:9], 11, v[198:199]
	v_bitop3_b32 v14, v0, 31, s33 bitop3:0xc8
	v_bfe_u32 v206, v0, 4, 2
	s_movk_i32 s4, 0x210
	v_lshl_or_b32 v8, v14, 4, v8
	v_ashrrev_i32_e32 v197, 31, v196
	v_and_b32_e32 v2, 56, v4
	v_and_b32_e32 v4, 0xf8, v4
	v_add3_u32 v229, 0, v5, v6
	v_mul_lo_u32 v5, v198, s4
	s_movk_i32 s4, 0x90
	v_or_b32_e32 v214, 4, v206
	v_lshl_add_u64 v[216:217], s[10:11], 0, v[8:9]
	v_lshlrev_b64 v[8:9], 14, v[196:197]
	v_bitop3_b32 v0, v0, 7, s33 bitop3:0xc8
	v_lshl_add_u32 v12, v4, 1, 0
	v_lshl_add_u32 v13, v2, 1, 0
	s_xor_b32 s16, s16, 0x80000000
	v_mul_u32_u24_e32 v3, 0x110, v206
	v_mul_lo_u32 v10, v196, s4
	v_mul_u32_u24_e32 v11, 0x110, v214
	v_lshl_or_b32 v8, v0, 4, v8
	s_mov_b32 s7, s37
	v_ashrrev_i32_e32 v201, 31, v200
	s_mov_b32 s17, s16
	s_mov_b32 s18, s16
	s_mov_b32 s19, s16
	s_mov_b32 s20, s16
	s_mov_b32 s21, s16
	s_mov_b32 s22, s16
	s_mov_b32 s23, s16
	s_mov_b32 s24, s16
	s_mov_b32 s25, s16
	s_mov_b32 s26, s16
	s_mov_b32 s27, s16
	s_mov_b32 s28, s16
	s_mov_b32 s29, s16
	s_mov_b32 s30, s16
	s_mov_b32 s31, s16
	s_lshl_b32 s53, s47, 4
	v_lshl_add_u64 v[218:219], s[10:11], 0, v[8:9]
	v_lshlrev_b32_e32 v208, 1, v4
	v_lshlrev_b32_e32 v220, 1, v2
	v_lshlrev_b32_e32 v222, 1, v6
	v_add_u32_e32 v197, v7, v6
	v_add_u32_e32 v230, v1, v3
	v_add_u32_e32 v231, v1, v11
	v_add_u32_e32 v232, v12, v5
	v_add_u32_e32 v233, v13, v10
.LBB0_847:
	s_lshl_b32 s4, s53, 1
	s_and_b32 s35, s4, 0x600
	s_lshl_b32 s4, s53, 14
	s_ashr_i32 s60, s47, 6
	s_and_b32 s50, s4, 0xc00000
	s_lshl_b32 s4, s47, 7
	s_ashr_i32 s61, s60, 31
	s_and_b32 s46, s4, 0x780
	s_lshl_b64 s[4:5], s[60:61], 8
	v_lshl_add_u64 v[2:3], s[4:5], 0, v[198:199]
	s_lshl_b32 s4, s47, 4
	s_and_b32 s34, s4, 0x300
	v_lshlrev_b64 v[2:3], 11, v[2:3]
	v_add_u32_e32 v4, s34, v196
	v_lshl_add_u64 v[2:3], s[58:59], 0, v[2:3]
	s_lshl_b32 s36, s34, 1
	v_ashrrev_i32_e32 v5, 31, v4
	v_lshl_add_u64 v[2:3], v[2:3], 0, s[36:37]
	v_lshlrev_b64 v[4:5], 14, v[4:5]
	v_lshl_add_u64 v[2:3], v[2:3], 0, v[208:209]
	v_lshl_add_u64 v[4:5], s[56:57], 0, v[4:5]
	s_lshl_b64 s[62:63], s[60:61], 9
	s_mov_b32 s4, 0x8000
	v_lshl_add_u64 v[4:5], v[4:5], 0, s[62:63]
	v_mov_b32_e32 v221, v209
	v_add_co_u32_e32 v6, vcc, s4, v2
	v_lshl_add_u64 v[4:5], v[4:5], 0, v[220:221]
	s_nop 0
	v_addc_co_u32_e32 v7, vcc, 0, v3, vcc
	s_mov_b32 s4, 0x100000
	global_load_dwordx4 v[96:99], v[2:3], off
	global_load_dwordx4 v[100:103], v[4:5], off
	global_load_dwordx4 v[104:107], v[6:7], off
	v_add_co_u32_e32 v6, vcc, s4, v4
	s_mov_b32 s4, 0x10000
	s_nop 0
	v_addc_co_u32_e32 v7, vcc, 0, v5, vcc
	global_load_dwordx4 v[108:111], v[6:7], off
	v_add_co_u32_e32 v6, vcc, s4, v2
	s_mov_b32 s4, 0x200000
	s_nop 0
	v_addc_co_u32_e32 v7, vcc, 0, v3, vcc
	global_load_dwordx4 v[112:115], v[6:7], off
	v_add_co_u32_e32 v6, vcc, s4, v4
	s_mov_b32 s4, 0x18000
	s_nop 0
	v_addc_co_u32_e32 v7, vcc, 0, v5, vcc
	v_add_co_u32_e32 v2, vcc, s4, v2
	v_add_u32_e32 v0, s46, v207
	s_nop 0
	v_addc_co_u32_e32 v3, vcc, 0, v3, vcc
	s_mov_b32 s4, 0x300000
	v_ashrrev_i32_e32 v1, 31, v0
	global_load_dwordx4 v[116:119], v[6:7], off
	global_load_dwordx4 v[120:123], v[2:3], off
	v_add_co_u32_e32 v2, vcc, s4, v4
	s_lshl_b64 s[4:5], s[60:61], 11
	v_lshl_add_u64 v[0:1], s[4:5], 0, v[0:1]
	v_lshlrev_b64 v[0:1], 11, v[0:1]
	v_lshl_add_u64 v[0:1], s[14:15], 0, v[0:1]
	v_lshl_add_u64 v[0:1], v[0:1], 0, s[36:37]
	v_mov_b32_e32 v223, v209
	v_addc_co_u32_e32 v3, vcc, 0, v5, vcc
	v_lshl_add_u64 v[0:1], v[0:1], 0, v[222:223]
	global_load_dwordx4 v[124:127], v[2:3], off
	global_load_dwordx4 v[56:59], v[0:1], off
	global_load_dwordx4 v[60:63], v[0:1], off offset:32
	global_load_dwordx4 v[36:39], v[0:1], off offset:64
	global_load_dwordx4 v[48:51], v[0:1], off offset:96
	global_load_dwordx4 v[52:55], v[0:1], off offset:128
	global_load_dwordx4 v[44:47], v[0:1], off offset:160
	global_load_dwordx4 v[40:43], v[0:1], off offset:192
	global_load_dwordx4 v[32:35], v[0:1], off offset:224
	global_load_dwordx4 v[28:31], v[0:1], off offset:256
	global_load_dwordx4 v[24:27], v[0:1], off offset:288
	global_load_dwordx4 v[20:23], v[0:1], off offset:320
	global_load_dwordx4 v[16:19], v[0:1], off offset:352
	global_load_dwordx4 v[12:15], v[0:1], off offset:384
	global_load_dwordx4 v[8:11], v[0:1], off offset:416
	global_load_dwordx4 v[4:7], v[0:1], off offset:448
	s_nop 0
	global_load_dwordx4 v[0:3], v[0:1], off offset:480
	s_lshl_b64 s[38:39], s[60:61], 19
	s_or_b32 s38, s38, s35
	v_lshl_add_u64 v[224:225], v[216:217], 0, s[38:39]
	s_add_u32 s38, s50, s62
	s_addc_u32 s39, 0, s63
	v_mov_b32_e32 v221, 0
	v_lshl_add_u64 v[226:227], v[218:219], 0, s[38:39]
	s_mov_b32 s35, 3
	s_waitcnt vmcnt(15)
	v_and_b32_e32 v132, 0xffff0000, v56
	v_lshlrev_b32_e32 v134, 16, v56
	v_mul_f32_e32 v169, v132, v132
	v_lshlrev_b32_e32 v130, 16, v57
	v_fmac_f32_e32 v169, v134, v134
	v_and_b32_e32 v128, 0xffff0000, v57
	v_fmac_f32_e32 v169, v130, v130
	v_lshlrev_b32_e32 v135, 16, v58
	v_fmac_f32_e32 v169, v128, v128
	v_and_b32_e32 v133, 0xffff0000, v58
	v_fmac_f32_e32 v169, v135, v135
	v_lshlrev_b32_e32 v131, 16, v59
	v_fmac_f32_e32 v169, v133, v133
	v_and_b32_e32 v129, 0xffff0000, v59
	v_fmac_f32_e32 v169, v131, v131
	v_fmac_f32_e32 v169, v129, v129
	s_waitcnt vmcnt(14)
	v_lshlrev_b32_e32 v142, 16, v60
	v_and_b32_e32 v140, 0xffff0000, v60
	v_fmac_f32_e32 v169, v142, v142
	v_lshlrev_b32_e32 v138, 16, v61
	v_fmac_f32_e32 v169, v140, v140
	v_and_b32_e32 v136, 0xffff0000, v61
	v_fmac_f32_e32 v169, v138, v138
	v_lshlrev_b32_e32 v153, 16, v62
	v_fmac_f32_e32 v169, v136, v136
	v_and_b32_e32 v141, 0xffff0000, v62
	v_fmac_f32_e32 v169, v153, v153
	v_lshlrev_b32_e32 v139, 16, v63
	v_fmac_f32_e32 v169, v141, v141
	v_and_b32_e32 v137, 0xffff0000, v63
	v_fmac_f32_e32 v169, v139, v139
	v_fmac_f32_e32 v169, v137, v137
	s_waitcnt vmcnt(13)
	v_lshlrev_b32_e32 v156, 16, v36
	v_and_b32_e32 v157, 0xffff0000, v36
	v_fmac_f32_e32 v169, v156, v156
	v_lshlrev_b32_e32 v155, 16, v37
	v_fmac_f32_e32 v169, v157, v157
	v_and_b32_e32 v154, 0xffff0000, v37
	v_fmac_f32_e32 v169, v155, v155
	v_lshlrev_b32_e32 v163, 16, v38
	v_fmac_f32_e32 v169, v154, v154
	v_and_b32_e32 v160, 0xffff0000, v38
	v_fmac_f32_e32 v169, v163, v163
	v_lshlrev_b32_e32 v168, 16, v39
	v_fmac_f32_e32 v169, v160, v160
	v_and_b32_e32 v167, 0xffff0000, v39
	v_fmac_f32_e32 v169, v168, v168
	v_fmac_f32_e32 v169, v167, v167
	s_waitcnt vmcnt(12)
	v_lshlrev_b32_e32 v166, 16, v48
	v_and_b32_e32 v164, 0xffff0000, v48
	v_fmac_f32_e32 v169, v166, v166
	v_lshlrev_b32_e32 v161, 16, v49
	v_fmac_f32_e32 v169, v164, v164
	v_and_b32_e32 v158, 0xffff0000, v49
	v_fmac_f32_e32 v169, v161, v161
	v_lshlrev_b32_e32 v165, 16, v50
	v_fmac_f32_e32 v169, v158, v158
	v_and_b32_e32 v162, 0xffff0000, v50
	v_fmac_f32_e32 v169, v165, v165
	v_lshlrev_b32_e32 v159, 16, v51
	v_fmac_f32_e32 v169, v162, v162
	v_and_b32_e32 v143, 0xffff0000, v51
	v_fmac_f32_e32 v169, v159, v159
	v_fmac_f32_e32 v169, v143, v143
	s_waitcnt vmcnt(11)
	v_lshlrev_b32_e32 v152, 16, v52
	v_and_b32_e32 v150, 0xffff0000, v52
	v_fmac_f32_e32 v169, v152, v152
	v_lshlrev_b32_e32 v147, 16, v53
	v_fmac_f32_e32 v169, v150, v150
	v_and_b32_e32 v145, 0xffff0000, v53
	v_fmac_f32_e32 v169, v147, v147
	v_lshlrev_b32_e32 v151, 16, v54
	v_fmac_f32_e32 v169, v145, v145
	v_and_b32_e32 v149, 0xffff0000, v54
	v_fmac_f32_e32 v169, v151, v151
	v_lshlrev_b32_e32 v146, 16, v55
	v_fmac_f32_e32 v169, v149, v149
	v_and_b32_e32 v144, 0xffff0000, v55
	v_fmac_f32_e32 v169, v146, v146
	v_fmac_f32_e32 v169, v144, v144
	s_waitcnt vmcnt(10)
	v_lshlrev_b32_e32 v148, 16, v44
	v_and_b32_e32 v94, 0xffff0000, v44
	v_fmac_f32_e32 v169, v148, v148
	v_lshlrev_b32_e32 v92, 16, v45
	v_fmac_f32_e32 v169, v94, v94
	v_and_b32_e32 v90, 0xffff0000, v45
	v_fmac_f32_e32 v169, v92, v92
	v_lshlrev_b32_e32 v95, 16, v46
	v_fmac_f32_e32 v169, v90, v90
	v_and_b32_e32 v93, 0xffff0000, v46
	v_fmac_f32_e32 v169, v95, v95
	v_lshlrev_b32_e32 v91, 16, v47
	v_fmac_f32_e32 v169, v93, v93
	v_and_b32_e32 v89, 0xffff0000, v47
	v_fmac_f32_e32 v169, v91, v91
	v_fmac_f32_e32 v169, v89, v89
	s_waitcnt vmcnt(9)
	v_lshlrev_b32_e32 v88, 16, v40
	v_and_b32_e32 v86, 0xffff0000, v40
	v_fmac_f32_e32 v169, v88, v88
	v_lshlrev_b32_e32 v84, 16, v41
	v_fmac_f32_e32 v169, v86, v86
	v_and_b32_e32 v82, 0xffff0000, v41
	v_fmac_f32_e32 v169, v84, v84
	v_lshlrev_b32_e32 v87, 16, v42
	v_fmac_f32_e32 v169, v82, v82
	v_and_b32_e32 v85, 0xffff0000, v42
	v_fmac_f32_e32 v169, v87, v87
	v_lshlrev_b32_e32 v83, 16, v43
	v_fmac_f32_e32 v169, v85, v85
	v_and_b32_e32 v81, 0xffff0000, v43
	v_fmac_f32_e32 v169, v83, v83
	v_fmac_f32_e32 v169, v81, v81
	s_waitcnt vmcnt(8)
	v_lshlrev_b32_e32 v80, 16, v32
	v_and_b32_e32 v78, 0xffff0000, v32
	v_fmac_f32_e32 v169, v80, v80
	v_lshlrev_b32_e32 v76, 16, v33
	v_fmac_f32_e32 v169, v78, v78
	v_and_b32_e32 v74, 0xffff0000, v33
	v_fmac_f32_e32 v169, v76, v76
	v_lshlrev_b32_e32 v79, 16, v34
	v_fmac_f32_e32 v169, v74, v74
	v_and_b32_e32 v77, 0xffff0000, v34
	v_fmac_f32_e32 v169, v79, v79
	v_lshlrev_b32_e32 v75, 16, v35
	v_fmac_f32_e32 v169, v77, v77
	v_and_b32_e32 v73, 0xffff0000, v35
	v_fmac_f32_e32 v169, v75, v75
	v_fmac_f32_e32 v169, v73, v73
	s_waitcnt vmcnt(7)
	v_lshlrev_b32_e32 v72, 16, v28
	v_and_b32_e32 v70, 0xffff0000, v28
	v_fmac_f32_e32 v169, v72, v72
	v_lshlrev_b32_e32 v68, 16, v29
	v_fmac_f32_e32 v169, v70, v70
	v_and_b32_e32 v66, 0xffff0000, v29
	v_fmac_f32_e32 v169, v68, v68
	v_lshlrev_b32_e32 v71, 16, v30
	v_fmac_f32_e32 v169, v66, v66
	v_and_b32_e32 v69, 0xffff0000, v30
	v_fmac_f32_e32 v169, v71, v71
	v_lshlrev_b32_e32 v67, 16, v31
	v_fmac_f32_e32 v169, v69, v69
	v_and_b32_e32 v65, 0xffff0000, v31
	v_fmac_f32_e32 v169, v67, v67
	v_fmac_f32_e32 v169, v65, v65
	s_waitcnt vmcnt(6)
	v_lshlrev_b32_e32 v64, 16, v24
	v_and_b32_e32 v62, 0xffff0000, v24
	v_fmac_f32_e32 v169, v64, v64
	v_lshlrev_b32_e32 v60, 16, v25
	v_fmac_f32_e32 v169, v62, v62
	v_and_b32_e32 v58, 0xffff0000, v25
	v_fmac_f32_e32 v169, v60, v60
	v_lshlrev_b32_e32 v63, 16, v26
	v_fmac_f32_e32 v169, v58, v58
	v_and_b32_e32 v61, 0xffff0000, v26
	v_fmac_f32_e32 v169, v63, v63
	v_lshlrev_b32_e32 v59, 16, v27
	v_fmac_f32_e32 v169, v61, v61
	v_and_b32_e32 v57, 0xffff0000, v27
	v_fmac_f32_e32 v169, v59, v59
	v_fmac_f32_e32 v169, v57, v57
	s_waitcnt vmcnt(5)
	v_lshlrev_b32_e32 v56, 16, v20
	v_and_b32_e32 v54, 0xffff0000, v20
	v_fmac_f32_e32 v169, v56, v56
	v_lshlrev_b32_e32 v52, 16, v21
	v_fmac_f32_e32 v169, v54, v54
	v_and_b32_e32 v50, 0xffff0000, v21
	v_fmac_f32_e32 v169, v52, v52
	v_lshlrev_b32_e32 v55, 16, v22
	v_fmac_f32_e32 v169, v50, v50
	v_and_b32_e32 v53, 0xffff0000, v22
	v_fmac_f32_e32 v169, v55, v55
	v_lshlrev_b32_e32 v51, 16, v23
	v_fmac_f32_e32 v169, v53, v53
	v_and_b32_e32 v49, 0xffff0000, v23
	v_fmac_f32_e32 v169, v51, v51
	v_fmac_f32_e32 v169, v49, v49
	s_waitcnt vmcnt(4)
	v_lshlrev_b32_e32 v48, 16, v16
	v_and_b32_e32 v46, 0xffff0000, v16
	v_fmac_f32_e32 v169, v48, v48
	v_lshlrev_b32_e32 v44, 16, v17
	v_fmac_f32_e32 v169, v46, v46
	v_and_b32_e32 v42, 0xffff0000, v17
	v_fmac_f32_e32 v169, v44, v44
	v_lshlrev_b32_e32 v47, 16, v18
	v_fmac_f32_e32 v169, v42, v42
	v_and_b32_e32 v45, 0xffff0000, v18
	v_fmac_f32_e32 v169, v47, v47
	v_lshlrev_b32_e32 v43, 16, v19
	v_fmac_f32_e32 v169, v45, v45
	v_and_b32_e32 v41, 0xffff0000, v19
	v_fmac_f32_e32 v169, v43, v43
	v_fmac_f32_e32 v169, v41, v41
	s_waitcnt vmcnt(3)
	v_lshlrev_b32_e32 v40, 16, v12
	v_and_b32_e32 v38, 0xffff0000, v12
	v_fmac_f32_e32 v169, v40, v40
	v_lshlrev_b32_e32 v36, 16, v13
	v_fmac_f32_e32 v169, v38, v38
	v_and_b32_e32 v34, 0xffff0000, v13
	v_fmac_f32_e32 v169, v36, v36
	v_lshlrev_b32_e32 v39, 16, v14
	v_fmac_f32_e32 v169, v34, v34
	v_and_b32_e32 v37, 0xffff0000, v14
	v_fmac_f32_e32 v169, v39, v39
	v_lshlrev_b32_e32 v35, 16, v15
	v_fmac_f32_e32 v169, v37, v37
	v_and_b32_e32 v33, 0xffff0000, v15
	v_fmac_f32_e32 v169, v35, v35
	v_fmac_f32_e32 v169, v33, v33
	s_waitcnt vmcnt(2)
	v_lshlrev_b32_e32 v32, 16, v8
	v_and_b32_e32 v30, 0xffff0000, v8
	v_fmac_f32_e32 v169, v32, v32
	v_lshlrev_b32_e32 v28, 16, v9
	v_fmac_f32_e32 v169, v30, v30
	v_and_b32_e32 v26, 0xffff0000, v9
	v_fmac_f32_e32 v169, v28, v28
	v_lshlrev_b32_e32 v31, 16, v10
	v_fmac_f32_e32 v169, v26, v26
	v_and_b32_e32 v29, 0xffff0000, v10
	v_fmac_f32_e32 v169, v31, v31
	v_lshlrev_b32_e32 v27, 16, v11
	v_fmac_f32_e32 v169, v29, v29
	v_and_b32_e32 v25, 0xffff0000, v11
	v_fmac_f32_e32 v169, v27, v27
	v_fmac_f32_e32 v169, v25, v25
	s_waitcnt vmcnt(1)
	v_lshlrev_b32_e32 v24, 16, v4
	v_and_b32_e32 v22, 0xffff0000, v4
	v_fmac_f32_e32 v169, v24, v24
	v_lshlrev_b32_e32 v20, 16, v5
	v_fmac_f32_e32 v169, v22, v22
	v_and_b32_e32 v19, 0xffff0000, v5
	v_fmac_f32_e32 v169, v20, v20
	v_lshlrev_b32_e32 v23, 16, v6
	v_fmac_f32_e32 v169, v19, v19
	v_and_b32_e32 v21, 0xffff0000, v6
	v_fmac_f32_e32 v169, v23, v23
	v_and_b32_e32 v16, 0xffff0000, v7
	v_lshlrev_b32_e32 v17, 16, v7
	v_fmac_f32_e32 v169, v21, v21
	v_pk_mul_f32 v[4:5], v[16:17], v[16:17]
	s_waitcnt vmcnt(0)
	v_and_b32_e32 v10, 0xffff0000, v0
	v_add_f32_e32 v5, v5, v169
	v_lshlrev_b32_e32 v11, 16, v0
	v_add_f32_e32 v6, v4, v5
	v_pk_mul_f32 v[4:5], v[10:11], v[10:11]
	v_and_b32_e32 v8, 0xffff0000, v1
	v_add_f32_e32 v0, v5, v6
	v_lshlrev_b32_e32 v9, 16, v1
	v_add_f32_e32 v4, v4, v0
	v_pk_mul_f32 v[0:1], v[8:9], v[8:9]
	v_and_b32_e32 v14, 0xffff0000, v2
	v_add_f32_e32 v1, v1, v4
	v_lshlrev_b32_e32 v15, 16, v2
	v_add_f32_e32 v4, v0, v1
	v_pk_mul_f32 v[0:1], v[14:15], v[14:15]
	v_and_b32_e32 v12, 0xffff0000, v3
	v_add_f32_e32 v1, v1, v4
	v_lshlrev_b32_e32 v13, 16, v3
	v_add_f32_e32 v2, v0, v1
	v_pk_mul_f32 v[0:1], v[12:13], v[12:13]
	s_nop 0
	v_add_f32_e32 v1, v1, v2
	v_add_f32_e32 v0, v0, v1
	ds_bpermute_b32 v1, v215, v0
	s_waitcnt lgkmcnt(0)
	v_add_f32_e32 v0, v0, v1
	v_fmamk_f32 v0, v0, 0x3b800000, v248
	v_cmp_gt_f32_e32 vcc, s97, v0
	v_mul_f32_e32 v1, 0x4b800000, v0
	s_nop 0
	v_cndmask_b32_e32 v0, v0, v1, vcc
	v_rsq_f32_e32 v0, v0
	s_nop 0
	v_mul_f32_e32 v1, 0x45800000, v0
	v_cndmask_b32_e32 v0, v0, v1, vcc
	v_mul_f32_e32 v18, 0x3db8aa3b, v0
	ds_read_b128 v[0:3], v202 offset:16
	ds_read_b128 v[4:7], v202
	s_waitcnt lgkmcnt(1)
	v_mul_f32_e32 v0, v0, v18
	s_waitcnt lgkmcnt(0)
	v_mul_f32_e32 v4, v4, v18
	v_mul_f32_e32 v5, v5, v18
	v_mul_f32_e32 v1, v1, v18
	v_mul_f32_e32 v6, v6, v18
	v_mul_f32_e32 v2, v2, v18
	v_mul_f32_e32 v7, v7, v18
	v_mul_f32_e32 v3, v3, v18
	v_mul_f32_e32 v4, v4, v134
	v_mul_f32_e32 v0, v0, v135
	v_mul_f32_e32 v5, v5, v132
	v_mul_f32_e32 v1, v1, v133
	v_mul_f32_e32 v6, v6, v130
	v_mul_f32_e32 v2, v2, v131
	v_mul_f32_e32 v7, v7, v128
	v_mul_f32_e32 v3, v3, v129
	v_cvt_pk_bf16_f32 v128, v4, v5
	v_cvt_pk_bf16_f32 v129, v6, v7
	v_cvt_pk_bf16_f32 v130, v0, v1
	v_cvt_pk_bf16_f32 v131, v2, v3
	ds_read_b128 v[0:3], v202 offset:80
	ds_read_b128 v[4:7], v202 offset:64
	s_waitcnt lgkmcnt(1)
	v_mul_f32_e32 v0, v0, v18
	s_waitcnt lgkmcnt(0)
	v_mul_f32_e32 v4, v4, v18
	v_mul_f32_e32 v5, v5, v18
	v_mul_f32_e32 v1, v1, v18
	v_mul_f32_e32 v6, v6, v18
	v_mul_f32_e32 v2, v2, v18
	v_mul_f32_e32 v7, v7, v18
	v_mul_f32_e32 v3, v3, v18
	v_mul_f32_e32 v4, v4, v142
	v_mul_f32_e32 v0, v0, v153
	v_mul_f32_e32 v5, v5, v140
	v_mul_f32_e32 v1, v1, v141
	v_mul_f32_e32 v6, v6, v138
	v_mul_f32_e32 v2, v2, v139
	v_mul_f32_e32 v7, v7, v136
	v_mul_f32_e32 v3, v3, v137
	v_cvt_pk_bf16_f32 v132, v4, v5
	v_cvt_pk_bf16_f32 v133, v6, v7
	v_cvt_pk_bf16_f32 v134, v0, v1
	v_cvt_pk_bf16_f32 v135, v2, v3
	ds_read_b128 v[0:3], v202 offset:144
	ds_read_b128 v[4:7], v202 offset:128
	s_waitcnt lgkmcnt(1)
	v_mul_f32_e32 v0, v0, v18
	s_waitcnt lgkmcnt(0)
	v_mul_f32_e32 v4, v4, v18
	v_mul_f32_e32 v5, v5, v18
	v_mul_f32_e32 v1, v1, v18
	v_mul_f32_e32 v6, v6, v18
	v_mul_f32_e32 v2, v2, v18
	v_mul_f32_e32 v7, v7, v18
	v_mul_f32_e32 v3, v3, v18
	v_mul_f32_e32 v4, v4, v156
	v_mul_f32_e32 v0, v0, v163
	v_mul_f32_e32 v5, v5, v157
	v_mul_f32_e32 v1, v1, v160
	v_mul_f32_e32 v6, v6, v155
	v_mul_f32_e32 v2, v2, v168
	v_mul_f32_e32 v7, v7, v154
	v_mul_f32_e32 v3, v3, v167
	v_cvt_pk_bf16_f32 v136, v4, v5
	v_cvt_pk_bf16_f32 v137, v6, v7
	v_cvt_pk_bf16_f32 v138, v0, v1
	v_cvt_pk_bf16_f32 v139, v2, v3
	ds_read_b128 v[0:3], v202 offset:208
	ds_read_b128 v[4:7], v202 offset:192
	s_waitcnt lgkmcnt(1)
	v_mul_f32_e32 v0, v0, v18
	s_waitcnt lgkmcnt(0)
	v_mul_f32_e32 v4, v4, v18
	v_mul_f32_e32 v5, v5, v18
	v_mul_f32_e32 v1, v1, v18
	v_mul_f32_e32 v6, v6, v18
	v_mul_f32_e32 v2, v2, v18
	v_mul_f32_e32 v7, v7, v18
	v_mul_f32_e32 v3, v3, v18
	v_mul_f32_e32 v4, v4, v166
	v_mul_f32_e32 v0, v0, v165
	v_mul_f32_e32 v5, v5, v164
	v_mul_f32_e32 v1, v1, v162
	v_mul_f32_e32 v6, v6, v161
	v_mul_f32_e32 v2, v2, v159
	v_mul_f32_e32 v7, v7, v158
	v_mul_f32_e32 v3, v3, v143
	v_cvt_pk_bf16_f32 v140, v4, v5
	v_cvt_pk_bf16_f32 v141, v6, v7
	v_cvt_pk_bf16_f32 v142, v0, v1
	v_cvt_pk_bf16_f32 v143, v2, v3
	ds_read_b128 v[0:3], v202 offset:272
	ds_read_b128 v[4:7], v202 offset:256
	s_waitcnt lgkmcnt(1)
	v_mul_f32_e32 v0, v0, v18
	s_waitcnt lgkmcnt(0)
	v_mul_f32_e32 v4, v4, v18
	v_mul_f32_e32 v5, v5, v18
	v_mul_f32_e32 v1, v1, v18
	v_mul_f32_e32 v6, v6, v18
	v_mul_f32_e32 v2, v2, v18
	v_mul_f32_e32 v7, v7, v18
	v_mul_f32_e32 v3, v3, v18
	v_mul_f32_e32 v4, v4, v152
	v_mul_f32_e32 v0, v0, v151
	v_mul_f32_e32 v5, v5, v150
	v_mul_f32_e32 v1, v1, v149
	v_mul_f32_e32 v6, v6, v147
	v_mul_f32_e32 v2, v2, v146
	v_mul_f32_e32 v7, v7, v145
	v_mul_f32_e32 v3, v3, v144
	v_cvt_pk_bf16_f32 v144, v4, v5
	v_cvt_pk_bf16_f32 v145, v6, v7
	v_cvt_pk_bf16_f32 v146, v0, v1
	v_cvt_pk_bf16_f32 v147, v2, v3
	ds_read_b128 v[0:3], v202 offset:336
	ds_read_b128 v[4:7], v202 offset:320
	s_waitcnt lgkmcnt(1)
	v_mul_f32_e32 v0, v0, v18
	s_waitcnt lgkmcnt(0)
	v_mul_f32_e32 v4, v4, v18
	v_mul_f32_e32 v5, v5, v18
	v_mul_f32_e32 v1, v1, v18
	v_mul_f32_e32 v6, v6, v18
	v_mul_f32_e32 v2, v2, v18
	v_mul_f32_e32 v7, v7, v18
	v_mul_f32_e32 v3, v3, v18
	v_mul_f32_e32 v4, v4, v148
	v_mul_f32_e32 v0, v0, v95
	v_mul_f32_e32 v5, v5, v94
	v_mul_f32_e32 v1, v1, v93
	v_mul_f32_e32 v6, v6, v92
	v_mul_f32_e32 v2, v2, v91
	v_mul_f32_e32 v7, v7, v90
	v_mul_f32_e32 v3, v3, v89
	v_cvt_pk_bf16_f32 v148, v4, v5
	v_cvt_pk_bf16_f32 v149, v6, v7
	v_cvt_pk_bf16_f32 v150, v0, v1
	v_cvt_pk_bf16_f32 v151, v2, v3
	ds_read_b128 v[0:3], v202 offset:400
	ds_read_b128 v[4:7], v202 offset:384
	s_waitcnt lgkmcnt(1)
	v_mul_f32_e32 v0, v0, v18
	s_waitcnt lgkmcnt(0)
	v_mul_f32_e32 v4, v4, v18
	v_mul_f32_e32 v5, v5, v18
	v_mul_f32_e32 v1, v1, v18
	v_mul_f32_e32 v6, v6, v18
	v_mul_f32_e32 v2, v2, v18
	v_mul_f32_e32 v7, v7, v18
	v_mul_f32_e32 v3, v3, v18
	v_mul_f32_e32 v4, v4, v88
	v_mul_f32_e32 v0, v0, v87
	v_mul_f32_e32 v5, v5, v86
	v_mul_f32_e32 v1, v1, v85
	v_mul_f32_e32 v6, v6, v84
	v_mul_f32_e32 v2, v2, v83
	v_mul_f32_e32 v7, v7, v82
	v_mul_f32_e32 v3, v3, v81
	v_cvt_pk_bf16_f32 v152, v4, v5
	v_cvt_pk_bf16_f32 v153, v6, v7
	v_cvt_pk_bf16_f32 v154, v0, v1
	v_cvt_pk_bf16_f32 v155, v2, v3
	ds_read_b128 v[0:3], v202 offset:464
	ds_read_b128 v[4:7], v202 offset:448
	s_waitcnt lgkmcnt(1)
	v_mul_f32_e32 v0, v0, v18
	s_waitcnt lgkmcnt(0)
	v_mul_f32_e32 v4, v4, v18
	v_mul_f32_e32 v5, v5, v18
	v_mul_f32_e32 v1, v1, v18
	v_mul_f32_e32 v6, v6, v18
	v_mul_f32_e32 v2, v2, v18
	v_mul_f32_e32 v7, v7, v18
	v_mul_f32_e32 v3, v3, v18
	v_mul_f32_e32 v4, v4, v80
	v_mul_f32_e32 v0, v0, v79
	v_mul_f32_e32 v5, v5, v78
	v_mul_f32_e32 v1, v1, v77
	v_mul_f32_e32 v6, v6, v76
	v_mul_f32_e32 v2, v2, v75
	v_mul_f32_e32 v7, v7, v74
	v_mul_f32_e32 v3, v3, v73
	v_cvt_pk_bf16_f32 v156, v4, v5
	v_cvt_pk_bf16_f32 v157, v6, v7
	v_cvt_pk_bf16_f32 v158, v0, v1
	v_cvt_pk_bf16_f32 v159, v2, v3
	ds_read_b128 v[0:3], v202 offset:528
	ds_read_b128 v[4:7], v202 offset:512
	s_waitcnt lgkmcnt(1)
	v_mul_f32_e32 v0, v0, v18
	s_waitcnt lgkmcnt(0)
	v_mul_f32_e32 v4, v4, v18
	v_mul_f32_e32 v5, v5, v18
	v_mul_f32_e32 v1, v1, v18
	v_mul_f32_e32 v6, v6, v18
	v_mul_f32_e32 v2, v2, v18
	v_mul_f32_e32 v7, v7, v18
	v_mul_f32_e32 v3, v3, v18
	v_mul_f32_e32 v4, v4, v72
	v_mul_f32_e32 v0, v0, v71
	v_mul_f32_e32 v5, v5, v70
	v_mul_f32_e32 v1, v1, v69
	v_mul_f32_e32 v6, v6, v68
	v_mul_f32_e32 v2, v2, v67
	v_mul_f32_e32 v7, v7, v66
	v_mul_f32_e32 v3, v3, v65
	v_cvt_pk_bf16_f32 v164, v4, v5
	v_cvt_pk_bf16_f32 v165, v6, v7
	v_cvt_pk_bf16_f32 v166, v0, v1
	v_cvt_pk_bf16_f32 v167, v2, v3
	ds_read_b128 v[0:3], v202 offset:592
	ds_read_b128 v[4:7], v202 offset:576
	s_waitcnt lgkmcnt(1)
	v_mul_f32_e32 v0, v0, v18
	s_waitcnt lgkmcnt(0)
	v_mul_f32_e32 v4, v4, v18
	v_mul_f32_e32 v5, v5, v18
	v_mul_f32_e32 v1, v1, v18
	v_mul_f32_e32 v6, v6, v18
	v_mul_f32_e32 v2, v2, v18
	v_mul_f32_e32 v7, v7, v18
	v_mul_f32_e32 v3, v3, v18
	v_mul_f32_e32 v4, v4, v64
	v_mul_f32_e32 v0, v0, v63
	v_mul_f32_e32 v5, v5, v62
	v_mul_f32_e32 v1, v1, v61
	v_mul_f32_e32 v6, v6, v60
	v_mul_f32_e32 v2, v2, v59
	v_mul_f32_e32 v7, v7, v58
	v_mul_f32_e32 v3, v3, v57
	v_cvt_pk_bf16_f32 v160, v4, v5
	v_cvt_pk_bf16_f32 v161, v6, v7
	v_cvt_pk_bf16_f32 v162, v0, v1
	v_cvt_pk_bf16_f32 v163, v2, v3
	ds_read_b128 v[0:3], v202 offset:656
	ds_read_b128 v[4:7], v202 offset:640
	v_mov_b32_e32 v57, v221
	v_mov_b32_e32 v58, v221
	v_mov_b32_e32 v59, v221
	v_mov_b32_e32 v60, v221
	v_mov_b32_e32 v61, v221
	v_mov_b32_e32 v62, v221
	v_mov_b32_e32 v63, v221
	s_waitcnt lgkmcnt(1)
	v_mul_f32_e32 v0, v0, v18
	s_waitcnt lgkmcnt(0)
	v_mul_f32_e32 v4, v4, v18
	v_mul_f32_e32 v5, v5, v18
	v_mul_f32_e32 v1, v1, v18
	v_mul_f32_e32 v6, v6, v18
	v_mul_f32_e32 v2, v2, v18
	v_mul_f32_e32 v7, v7, v18
	v_mul_f32_e32 v3, v3, v18
	v_mul_f32_e32 v4, v4, v56
	v_mul_f32_e32 v0, v0, v55
	v_mul_f32_e32 v5, v5, v54
	v_mul_f32_e32 v1, v1, v53
	v_mul_f32_e32 v6, v6, v52
	v_mul_f32_e32 v2, v2, v51
	v_mul_f32_e32 v7, v7, v50
	v_mul_f32_e32 v3, v3, v49
	v_cvt_pk_bf16_f32 v168, v4, v5
	v_cvt_pk_bf16_f32 v169, v6, v7
	v_cvt_pk_bf16_f32 v170, v0, v1
	v_cvt_pk_bf16_f32 v171, v2, v3
	ds_read_b128 v[0:3], v202 offset:720
	ds_read_b128 v[4:7], v202 offset:704
	v_mov_b32_e32 v49, v221
	v_mov_b32_e32 v50, v221
	v_mov_b32_e32 v51, v221
	v_mov_b32_e32 v52, v221
	v_mov_b32_e32 v53, v221
	v_mov_b32_e32 v54, v221
	v_mov_b32_e32 v55, v221
	v_mov_b32_e32 v56, v221
	s_waitcnt lgkmcnt(1)
	v_mul_f32_e32 v0, v0, v18
	s_waitcnt lgkmcnt(0)
	v_mul_f32_e32 v4, v4, v18
	v_mul_f32_e32 v5, v5, v18
	v_mul_f32_e32 v1, v1, v18
	v_mul_f32_e32 v6, v6, v18
	v_mul_f32_e32 v2, v2, v18
	v_mul_f32_e32 v7, v7, v18
	v_mul_f32_e32 v3, v3, v18
	v_mul_f32_e32 v4, v4, v48
	v_mul_f32_e32 v0, v0, v47
	v_mul_f32_e32 v5, v5, v46
	v_mul_f32_e32 v1, v1, v45
	v_mul_f32_e32 v6, v6, v44
	v_mul_f32_e32 v2, v2, v43
	v_mul_f32_e32 v7, v7, v42
	v_mul_f32_e32 v3, v3, v41
	v_cvt_pk_bf16_f32 v172, v4, v5
	v_cvt_pk_bf16_f32 v173, v6, v7
	v_cvt_pk_bf16_f32 v174, v0, v1
	v_cvt_pk_bf16_f32 v175, v2, v3
	ds_read_b128 v[0:3], v202 offset:784
	ds_read_b128 v[4:7], v202 offset:768
	v_mov_b32_e32 v41, v221
	v_mov_b32_e32 v42, v221
	v_mov_b32_e32 v43, v221
	v_mov_b32_e32 v44, v221
	v_mov_b32_e32 v45, v221
	v_mov_b32_e32 v46, v221
	v_mov_b32_e32 v47, v221
	v_mov_b32_e32 v48, 0
	s_waitcnt lgkmcnt(1)
	v_mul_f32_e32 v0, v0, v18
	s_waitcnt lgkmcnt(0)
	v_mul_f32_e32 v4, v4, v18
	v_mul_f32_e32 v5, v5, v18
	v_mul_f32_e32 v1, v1, v18
	v_mul_f32_e32 v6, v6, v18
	v_mul_f32_e32 v2, v2, v18
	v_mul_f32_e32 v7, v7, v18
	v_mul_f32_e32 v3, v3, v18
	v_mul_f32_e32 v4, v4, v40
	v_mul_f32_e32 v0, v0, v39
	v_mul_f32_e32 v5, v5, v38
	v_mul_f32_e32 v1, v1, v37
	v_mul_f32_e32 v6, v6, v36
	v_mul_f32_e32 v2, v2, v35
	v_mul_f32_e32 v7, v7, v34
	v_mul_f32_e32 v3, v3, v33
	v_cvt_pk_bf16_f32 v176, v4, v5
	v_cvt_pk_bf16_f32 v177, v6, v7
	v_cvt_pk_bf16_f32 v178, v0, v1
	v_cvt_pk_bf16_f32 v179, v2, v3
	ds_read_b128 v[0:3], v202 offset:848
	ds_read_b128 v[4:7], v202 offset:832
	v_mov_b32_e32 v33, v221
	v_mov_b32_e32 v34, v221
	v_mov_b32_e32 v35, v221
	v_mov_b32_e32 v36, v221
	v_mov_b32_e32 v37, v221
	v_mov_b32_e32 v38, v221
	v_mov_b32_e32 v39, v221
	v_mov_b32_e32 v40, v221
	s_waitcnt lgkmcnt(1)
	v_mul_f32_e32 v0, v0, v18
	s_waitcnt lgkmcnt(0)
	v_mul_f32_e32 v4, v4, v18
	v_mul_f32_e32 v5, v5, v18
	v_mul_f32_e32 v1, v1, v18
	v_mul_f32_e32 v6, v6, v18
	v_mul_f32_e32 v2, v2, v18
	v_mul_f32_e32 v7, v7, v18
	v_mul_f32_e32 v3, v3, v18
	v_mul_f32_e32 v4, v4, v32
	v_mul_f32_e32 v0, v0, v31
	v_mul_f32_e32 v5, v5, v30
	v_mul_f32_e32 v1, v1, v29
	v_mul_f32_e32 v6, v6, v28
	v_mul_f32_e32 v2, v2, v27
	v_mul_f32_e32 v7, v7, v26
	v_mul_f32_e32 v3, v3, v25
	v_cvt_pk_bf16_f32 v180, v4, v5
	v_cvt_pk_bf16_f32 v181, v6, v7
	v_cvt_pk_bf16_f32 v182, v0, v1
	v_cvt_pk_bf16_f32 v183, v2, v3
	ds_read_b128 v[0:3], v202 offset:912
	ds_read_b128 v[4:7], v202 offset:896
	v_mov_b32_e32 v25, v221
	v_mov_b32_e32 v26, v221
	v_mov_b32_e32 v27, v221
	v_mov_b32_e32 v28, v221
	v_mov_b32_e32 v29, v221
	v_mov_b32_e32 v30, v221
	v_mov_b32_e32 v31, v221
	v_mov_b32_e32 v32, 0
	s_waitcnt lgkmcnt(1)
	v_mul_f32_e32 v0, v0, v18
	s_waitcnt lgkmcnt(0)
	v_mul_f32_e32 v4, v4, v18
	v_mul_f32_e32 v5, v5, v18
	v_mul_f32_e32 v1, v1, v18
	v_mul_f32_e32 v6, v6, v18
	v_mul_f32_e32 v2, v2, v18
	v_mul_f32_e32 v7, v7, v18
	v_mul_f32_e32 v3, v3, v18
	v_mul_f32_e32 v4, v4, v24
	v_mul_f32_e32 v0, v0, v23
	v_mul_f32_e32 v5, v5, v22
	v_mul_f32_e32 v1, v1, v21
	v_mul_f32_e32 v6, v6, v20
	v_mul_f32_e32 v2, v2, v17
	v_mul_f32_e32 v7, v7, v19
	v_mul_f32_e32 v3, v3, v16
	v_cvt_pk_bf16_f32 v184, v4, v5
	v_cvt_pk_bf16_f32 v185, v6, v7
	v_cvt_pk_bf16_f32 v186, v0, v1
	v_cvt_pk_bf16_f32 v187, v2, v3
	ds_read_b128 v[0:3], v202 offset:976
	ds_read_b128 v[4:7], v202 offset:960
	v_mov_b32_e32 v16, 0
	v_mov_b32_e32 v17, v221
	v_mov_b32_e32 v19, v221
	v_mov_b32_e32 v20, v221
	v_mov_b32_e32 v21, v221
	v_mov_b32_e32 v22, v221
	v_mov_b32_e32 v23, v221
	v_mov_b32_e32 v24, v221
	s_waitcnt lgkmcnt(1)
	v_mul_f32_e32 v0, v0, v18
	s_waitcnt lgkmcnt(0)
	v_mul_f32_e32 v4, v4, v18
	v_mul_f32_e32 v5, v5, v18
	v_mul_f32_e32 v1, v1, v18
	v_mul_f32_e32 v6, v6, v18
	v_mul_f32_e32 v2, v2, v18
	v_mul_f32_e32 v7, v7, v18
	v_mul_f32_e32 v3, v3, v18
	v_mul_f32_e32 v4, v4, v11
	v_mul_f32_e32 v0, v0, v15
	v_mul_f32_e32 v5, v5, v10
	v_mul_f32_e32 v1, v1, v14
	v_mul_f32_e32 v6, v6, v9
	v_mul_f32_e32 v2, v2, v13
	v_mul_f32_e32 v7, v7, v8
	v_mul_f32_e32 v3, v3, v12
	v_cvt_pk_bf16_f32 v188, v4, v5
	v_cvt_pk_bf16_f32 v189, v6, v7
	v_cvt_pk_bf16_f32 v190, v0, v1
	v_cvt_pk_bf16_f32 v191, v2, v3
	v_mov_b32_e32 v0, 0
	v_mov_b32_e32 v1, v221
	v_mov_b32_e32 v2, v221
	v_mov_b32_e32 v3, v221
	v_mov_b32_e32 v4, v221
	v_mov_b32_e32 v5, v221
	v_mov_b32_e32 v6, v221
	v_mov_b32_e32 v7, v221
	v_mov_b32_e32 v8, v221
	v_mov_b32_e32 v9, v221
	v_mov_b32_e32 v10, v221
	v_mov_b32_e32 v11, v221
	v_mov_b32_e32 v12, v221
	v_mov_b32_e32 v13, v221
	v_mov_b32_e32 v14, v221
	v_mov_b32_e32 v15, v221
	v_mov_b32_e32 v18, v221
